# wf_task (folded Fourier weight precompute, f32) core rewritten on v_mfma_f32_16x16x4_f32: exact f32 fma chains, twiddles from the LDS cosine table
# speedup vs baseline: 1.0634x; 1.0080x over previous
; __device__ void wf_task(int wv, const Params& p, int task, float* ldsf) {
;     ...
;     const int n = tid & 63, wvl = __builtin_amdgcn_readfirstlane(tid >> 6);
;     float ac[16], as[16];
; #pragma unroll
;     for (int c = 0; c < 16; ++c) { ac[c] = 0.f; as[c] = 0.f; }
;     for (int cq = 0; cq < 128; ++cq) { const float v = tile[cq * 64 + n];
; #pragma unroll
;         for (int cc = 0; cc < 16; ++cc) { const int idx = ((wvl * 16 + cc) * cq) & 127; ac[cc] += ct[idx] * v; as[cc] += ct[(idx + 96) & 127] * v; } }
;     float* Wf = (float*)(p.ws + WS_WF32);
; #pragma unroll
;     for (int cc = 0; cc < 16; ++cc) { const int c = wvl * 16 + cc; Wf[(size_t)(g * 128 + c) * DM + n0 + n] = ac[cc]; Wf[(size_t)(1024 + g * 128 + c) * DM + n0 + n] = as[cc]; }
.LBB0_30:
	s_or_b64 exec, exec, s[0:1]
	v_readfirstlane_b32 s0, v4
	s_ashr_i32 s0, s0, 2
	v_and_b32_e32 v35, 63, v4
	s_and_b32 s38, s0, -16
	v_mov_b32_e32 v2, 0
	s_mov_b32 s39, 0
	v_lshl_add_u32 v36, v35, 2, 0
	s_or_b32 s0, s0, 15
	s_or_b32 s37, s38, 1
	s_or_b32 s36, s38, 2
	s_or_b32 s17, s38, 3
	s_or_b32 s16, s38, 4
	s_or_b32 s15, s38, 5
	s_or_b32 s14, s38, 6
	s_or_b32 s13, s38, 7
	s_or_b32 s12, s38, 8
	s_or_b32 s9, s38, 9
	s_or_b32 s8, s38, 10
	s_or_b32 s5, s38, 11
	s_or_b32 s4, s38, 12
	s_or_b32 s3, s38, 13
	s_or_b32 s1, s38, 14
	s_movk_i32 s40, 0x60
	s_mov_b32 s43, 0
	s_mov_b32 s44, 0
	s_mov_b32 s45, 0
	s_mov_b32 s46, 0
	s_mov_b32 s47, 0
	s_mov_b32 s48, 0
	s_mov_b32 s49, 0
	s_mov_b32 s50, 0
	s_mov_b32 s51, 0
	s_mov_b32 s52, 0
	s_mov_b32 s53, 0
	s_mov_b32 s54, 0
	s_mov_b32 s55, 0
	s_mov_b32 s56, 0
	s_mov_b32 s57, 0
	v_mov_b32_e32 v3, v2
	v_mov_b32_e32 v6, v2
	v_mov_b32_e32 v7, v2
	v_mov_b32_e32 v10, v2
	v_mov_b32_e32 v11, v2
	v_mov_b32_e32 v14, v2
	v_mov_b32_e32 v15, v2
	v_mov_b32_e32 v18, v2
	v_mov_b32_e32 v19, v2
	v_mov_b32_e32 v22, v2
	v_mov_b32_e32 v23, v2
	v_mov_b32_e32 v26, v2
	v_mov_b32_e32 v27, v2
	v_mov_b32_e32 v30, v2
	v_mov_b32_e32 v31, v2
	v_mov_b32_e32 v4, v2
	v_mov_b32_e32 v5, v2
	v_mov_b32_e32 v8, v2
	v_mov_b32_e32 v9, v2
	v_mov_b32_e32 v12, v2
	v_mov_b32_e32 v13, v2
	v_mov_b32_e32 v16, v2
	v_mov_b32_e32 v17, v2
	v_mov_b32_e32 v20, v2
	v_mov_b32_e32 v21, v2
	v_mov_b32_e32 v24, v2
	v_mov_b32_e32 v25, v2
	v_mov_b32_e32 v28, v2
	v_mov_b32_e32 v29, v2
	v_mov_b32_e32 v32, v2
	v_mov_b32_e32 v33, v2
	s_waitcnt lgkmcnt(0)
	s_barrier
	v_mbcnt_lo_u32_b32 v54, -1, 0
	v_mbcnt_hi_u32_b32 v54, -1, v54
	v_and_b32_e32 v55, 15, v54
	v_lshrrev_b32_e32 v56, 4, v54
	s_lshl_b32 s38, s33, 4
	v_add_u32_e32 v48, s38, v55
	v_mul_lo_u32 v46, v48, v56
	v_lshlrev_b32_e32 v46, 2, v46
	v_and_b32_e32 v46, 0x1fc, v46
	v_lshlrev_b32_e32 v48, 4, v48
	v_lshlrev_b32_e32 v49, 8, v56
	v_lshl_add_u32 v49, v55, 2, v49
	v_mov_b32_e32 v2, 0
	v_mov_b32_e32 v18, 0
	v_mov_b32_e32 v3, 0
	v_mov_b32_e32 v19, 0
	v_mov_b32_e32 v4, 0
	v_mov_b32_e32 v20, 0
	v_mov_b32_e32 v5, 0
	v_mov_b32_e32 v21, 0
	v_mov_b32_e32 v6, 0
	v_mov_b32_e32 v22, 0
	v_mov_b32_e32 v7, 0
	v_mov_b32_e32 v23, 0
	v_mov_b32_e32 v8, 0
	v_mov_b32_e32 v24, 0
	v_mov_b32_e32 v9, 0
	v_mov_b32_e32 v25, 0
	v_mov_b32_e32 v10, 0
	v_mov_b32_e32 v26, 0
	v_mov_b32_e32 v11, 0
	v_mov_b32_e32 v27, 0
	v_mov_b32_e32 v12, 0
	v_mov_b32_e32 v28, 0
	v_mov_b32_e32 v13, 0
	v_mov_b32_e32 v29, 0
	v_mov_b32_e32 v14, 0
	v_mov_b32_e32 v30, 0
	v_mov_b32_e32 v15, 0
	v_mov_b32_e32 v31, 0
	v_mov_b32_e32 v16, 0
	v_mov_b32_e32 v32, 0
	v_mov_b32_e32 v17, 0
	v_mov_b32_e32 v33, 0
	v_add_u32_e32 v47, 0x180, v46
	v_and_b32_e32 v47, 0x1fc, v47
	ds_read_b32 v34, v46 offset:32768
	ds_read_b32 v35, v47 offset:32768
	ds_read_b32 v38, v49 offset:0
	ds_read_b32 v39, v49 offset:64
	ds_read_b32 v40, v49 offset:128
	ds_read_b32 v41, v49 offset:192
	v_add_u32_e32 v46, v46, v48
	v_and_b32_e32 v46, 0x1fc, v46
	v_add_u32_e32 v47, 0x180, v46
	v_and_b32_e32 v47, 0x1fc, v47
	ds_read_b32 v36, v46 offset:32768
	ds_read_b32 v37, v47 offset:32768
	ds_read_b32 v42, v49 offset:1024
	ds_read_b32 v43, v49 offset:1088
	ds_read_b32 v44, v49 offset:1152
	ds_read_b32 v45, v49 offset:1216
	s_waitcnt lgkmcnt(6)
	v_mfma_f32_16x16x4_f32 v[2:5], v34, v38, v[2:5]
	v_mfma_f32_16x16x4_f32 v[18:21], v35, v38, v[18:21]
	v_mfma_f32_16x16x4_f32 v[6:9], v34, v39, v[6:9]
	v_mfma_f32_16x16x4_f32 v[22:25], v35, v39, v[22:25]
	v_mfma_f32_16x16x4_f32 v[10:13], v34, v40, v[10:13]
	v_mfma_f32_16x16x4_f32 v[26:29], v35, v40, v[26:29]
	v_mfma_f32_16x16x4_f32 v[14:17], v34, v41, v[14:17]
	v_mfma_f32_16x16x4_f32 v[30:33], v35, v41, v[30:33]
	v_add_u32_e32 v46, v46, v48
	v_and_b32_e32 v46, 0x1fc, v46
	v_add_u32_e32 v47, 0x180, v46
	v_and_b32_e32 v47, 0x1fc, v47
	ds_read_b32 v34, v46 offset:32768
	ds_read_b32 v35, v47 offset:32768
	ds_read_b32 v38, v49 offset:2048
	ds_read_b32 v39, v49 offset:2112
	ds_read_b32 v40, v49 offset:2176
	ds_read_b32 v41, v49 offset:2240
	s_waitcnt lgkmcnt(6)
	v_mfma_f32_16x16x4_f32 v[2:5], v36, v42, v[2:5]
	v_mfma_f32_16x16x4_f32 v[18:21], v37, v42, v[18:21]
	v_mfma_f32_16x16x4_f32 v[6:9], v36, v43, v[6:9]
	v_mfma_f32_16x16x4_f32 v[22:25], v37, v43, v[22:25]
	v_mfma_f32_16x16x4_f32 v[10:13], v36, v44, v[10:13]
	v_mfma_f32_16x16x4_f32 v[26:29], v37, v44, v[26:29]
	v_mfma_f32_16x16x4_f32 v[14:17], v36, v45, v[14:17]
	v_mfma_f32_16x16x4_f32 v[30:33], v37, v45, v[30:33]
	v_add_u32_e32 v46, v46, v48
	v_and_b32_e32 v46, 0x1fc, v46
	v_add_u32_e32 v47, 0x180, v46
	v_and_b32_e32 v47, 0x1fc, v47
	ds_read_b32 v36, v46 offset:32768
	ds_read_b32 v37, v47 offset:32768
	ds_read_b32 v42, v49 offset:3072
	ds_read_b32 v43, v49 offset:3136
	ds_read_b32 v44, v49 offset:3200
	ds_read_b32 v45, v49 offset:3264
	s_waitcnt lgkmcnt(6)
	v_mfma_f32_16x16x4_f32 v[2:5], v34, v38, v[2:5]
	v_mfma_f32_16x16x4_f32 v[18:21], v35, v38, v[18:21]
	v_mfma_f32_16x16x4_f32 v[6:9], v34, v39, v[6:9]
	v_mfma_f32_16x16x4_f32 v[22:25], v35, v39, v[22:25]
	v_mfma_f32_16x16x4_f32 v[10:13], v34, v40, v[10:13]
	v_mfma_f32_16x16x4_f32 v[26:29], v35, v40, v[26:29]
	v_mfma_f32_16x16x4_f32 v[14:17], v34, v41, v[14:17]
	v_mfma_f32_16x16x4_f32 v[30:33], v35, v41, v[30:33]
	v_add_u32_e32 v46, v46, v48
	v_and_b32_e32 v46, 0x1fc, v46
	v_add_u32_e32 v47, 0x180, v46
	v_and_b32_e32 v47, 0x1fc, v47
	ds_read_b32 v34, v46 offset:32768
	ds_read_b32 v35, v47 offset:32768
	ds_read_b32 v38, v49 offset:4096
	ds_read_b32 v39, v49 offset:4160
	ds_read_b32 v40, v49 offset:4224
	ds_read_b32 v41, v49 offset:4288
	s_waitcnt lgkmcnt(6)
; __device__ void wf_task(int wv, const Params& p, int task, float* ldsf) {
;     ...
;     for (int cq = 0; cq < 128; ++cq) { const float v = tile[cq * 64 + n];
; #pragma unroll
;         for (int cc = 0; cc < 16; ++cc) { const int idx = ((wvl * 16 + cc) * cq) & 127; ac[cc] += ct[idx] * v; as[cc] += ct[(idx + 96) & 127] * v; } }
	v_mfma_f32_16x16x4_f32 v[2:5], v36, v42, v[2:5]
	v_mfma_f32_16x16x4_f32 v[18:21], v37, v42, v[18:21]
	v_mfma_f32_16x16x4_f32 v[6:9], v36, v43, v[6:9]
	v_mfma_f32_16x16x4_f32 v[22:25], v37, v43, v[22:25]
	v_mfma_f32_16x16x4_f32 v[10:13], v36, v44, v[10:13]
	v_mfma_f32_16x16x4_f32 v[26:29], v37, v44, v[26:29]
	v_mfma_f32_16x16x4_f32 v[14:17], v36, v45, v[14:17]
	v_mfma_f32_16x16x4_f32 v[30:33], v37, v45, v[30:33]
	v_add_u32_e32 v46, v46, v48
	v_and_b32_e32 v46, 0x1fc, v46
	v_add_u32_e32 v47, 0x180, v46
	v_and_b32_e32 v47, 0x1fc, v47
	ds_read_b32 v36, v46 offset:32768
	ds_read_b32 v37, v47 offset:32768
	ds_read_b32 v42, v49 offset:5120
	ds_read_b32 v43, v49 offset:5184
	ds_read_b32 v44, v49 offset:5248
	ds_read_b32 v45, v49 offset:5312
	s_waitcnt lgkmcnt(6)
	v_mfma_f32_16x16x4_f32 v[2:5], v34, v38, v[2:5]
	v_mfma_f32_16x16x4_f32 v[18:21], v35, v38, v[18:21]
	v_mfma_f32_16x16x4_f32 v[6:9], v34, v39, v[6:9]
	v_mfma_f32_16x16x4_f32 v[22:25], v35, v39, v[22:25]
	v_mfma_f32_16x16x4_f32 v[10:13], v34, v40, v[10:13]
	v_mfma_f32_16x16x4_f32 v[26:29], v35, v40, v[26:29]
	v_mfma_f32_16x16x4_f32 v[14:17], v34, v41, v[14:17]
	v_mfma_f32_16x16x4_f32 v[30:33], v35, v41, v[30:33]
	v_add_u32_e32 v46, v46, v48
	v_and_b32_e32 v46, 0x1fc, v46
	v_add_u32_e32 v47, 0x180, v46
	v_and_b32_e32 v47, 0x1fc, v47
	ds_read_b32 v34, v46 offset:32768
	ds_read_b32 v35, v47 offset:32768
	ds_read_b32 v38, v49 offset:6144
	ds_read_b32 v39, v49 offset:6208
	ds_read_b32 v40, v49 offset:6272
	ds_read_b32 v41, v49 offset:6336
	s_waitcnt lgkmcnt(6)
	v_mfma_f32_16x16x4_f32 v[2:5], v36, v42, v[2:5]
	v_mfma_f32_16x16x4_f32 v[18:21], v37, v42, v[18:21]
	v_mfma_f32_16x16x4_f32 v[6:9], v36, v43, v[6:9]
	v_mfma_f32_16x16x4_f32 v[22:25], v37, v43, v[22:25]
	v_mfma_f32_16x16x4_f32 v[10:13], v36, v44, v[10:13]
	v_mfma_f32_16x16x4_f32 v[26:29], v37, v44, v[26:29]
	v_mfma_f32_16x16x4_f32 v[14:17], v36, v45, v[14:17]
	v_mfma_f32_16x16x4_f32 v[30:33], v37, v45, v[30:33]
	v_add_u32_e32 v46, v46, v48
	v_and_b32_e32 v46, 0x1fc, v46
	v_add_u32_e32 v47, 0x180, v46
	v_and_b32_e32 v47, 0x1fc, v47
	ds_read_b32 v36, v46 offset:32768
	ds_read_b32 v37, v47 offset:32768
	ds_read_b32 v42, v49 offset:7168
	ds_read_b32 v43, v49 offset:7232
	ds_read_b32 v44, v49 offset:7296
	ds_read_b32 v45, v49 offset:7360
	s_waitcnt lgkmcnt(6)
	v_mfma_f32_16x16x4_f32 v[2:5], v34, v38, v[2:5]
	v_mfma_f32_16x16x4_f32 v[18:21], v35, v38, v[18:21]
	v_mfma_f32_16x16x4_f32 v[6:9], v34, v39, v[6:9]
	v_mfma_f32_16x16x4_f32 v[22:25], v35, v39, v[22:25]
	v_mfma_f32_16x16x4_f32 v[10:13], v34, v40, v[10:13]
	v_mfma_f32_16x16x4_f32 v[26:29], v35, v40, v[26:29]
	v_mfma_f32_16x16x4_f32 v[14:17], v34, v41, v[14:17]
	v_mfma_f32_16x16x4_f32 v[30:33], v35, v41, v[30:33]
	v_add_u32_e32 v46, v46, v48
	v_and_b32_e32 v46, 0x1fc, v46
	v_add_u32_e32 v47, 0x180, v46
	v_and_b32_e32 v47, 0x1fc, v47
	ds_read_b32 v34, v46 offset:32768
	ds_read_b32 v35, v47 offset:32768
	ds_read_b32 v38, v49 offset:8192
	ds_read_b32 v39, v49 offset:8256
	ds_read_b32 v40, v49 offset:8320
	ds_read_b32 v41, v49 offset:8384
	s_waitcnt lgkmcnt(6)
	v_mfma_f32_16x16x4_f32 v[2:5], v36, v42, v[2:5]
	v_mfma_f32_16x16x4_f32 v[18:21], v37, v42, v[18:21]
	v_mfma_f32_16x16x4_f32 v[6:9], v36, v43, v[6:9]
	v_mfma_f32_16x16x4_f32 v[22:25], v37, v43, v[22:25]
	v_mfma_f32_16x16x4_f32 v[10:13], v36, v44, v[10:13]
	v_mfma_f32_16x16x4_f32 v[26:29], v37, v44, v[26:29]
	v_mfma_f32_16x16x4_f32 v[14:17], v36, v45, v[14:17]
	v_mfma_f32_16x16x4_f32 v[30:33], v37, v45, v[30:33]
	v_add_u32_e32 v46, v46, v48
	v_and_b32_e32 v46, 0x1fc, v46
	v_add_u32_e32 v47, 0x180, v46
	v_and_b32_e32 v47, 0x1fc, v47
	ds_read_b32 v36, v46 offset:32768
	ds_read_b32 v37, v47 offset:32768
	ds_read_b32 v42, v49 offset:9216
	ds_read_b32 v43, v49 offset:9280
	ds_read_b32 v44, v49 offset:9344
	ds_read_b32 v45, v49 offset:9408
	s_waitcnt lgkmcnt(6)
	v_mfma_f32_16x16x4_f32 v[2:5], v34, v38, v[2:5]
	v_mfma_f32_16x16x4_f32 v[18:21], v35, v38, v[18:21]
	v_mfma_f32_16x16x4_f32 v[6:9], v34, v39, v[6:9]
	v_mfma_f32_16x16x4_f32 v[22:25], v35, v39, v[22:25]
	v_mfma_f32_16x16x4_f32 v[10:13], v34, v40, v[10:13]
	v_mfma_f32_16x16x4_f32 v[26:29], v35, v40, v[26:29]
	v_mfma_f32_16x16x4_f32 v[14:17], v34, v41, v[14:17]
	v_mfma_f32_16x16x4_f32 v[30:33], v35, v41, v[30:33]
	v_add_u32_e32 v46, v46, v48
	v_and_b32_e32 v46, 0x1fc, v46
	v_add_u32_e32 v47, 0x180, v46
	v_and_b32_e32 v47, 0x1fc, v47
	ds_read_b32 v34, v46 offset:32768
	ds_read_b32 v35, v47 offset:32768
	ds_read_b32 v38, v49 offset:10240
	ds_read_b32 v39, v49 offset:10304
	ds_read_b32 v40, v49 offset:10368
	ds_read_b32 v41, v49 offset:10432
	s_waitcnt lgkmcnt(6)
	v_mfma_f32_16x16x4_f32 v[2:5], v36, v42, v[2:5]
	v_mfma_f32_16x16x4_f32 v[18:21], v37, v42, v[18:21]
	v_mfma_f32_16x16x4_f32 v[6:9], v36, v43, v[6:9]
	v_mfma_f32_16x16x4_f32 v[22:25], v37, v43, v[22:25]
	v_mfma_f32_16x16x4_f32 v[10:13], v36, v44, v[10:13]
	v_mfma_f32_16x16x4_f32 v[26:29], v37, v44, v[26:29]
	v_mfma_f32_16x16x4_f32 v[14:17], v36, v45, v[14:17]
	v_mfma_f32_16x16x4_f32 v[30:33], v37, v45, v[30:33]
	v_add_u32_e32 v46, v46, v48
	v_and_b32_e32 v46, 0x1fc, v46
	v_add_u32_e32 v47, 0x180, v46
	v_and_b32_e32 v47, 0x1fc, v47
	ds_read_b32 v36, v46 offset:32768
	ds_read_b32 v37, v47 offset:32768
	ds_read_b32 v42, v49 offset:11264
	ds_read_b32 v43, v49 offset:11328
	ds_read_b32 v44, v49 offset:11392
	ds_read_b32 v45, v49 offset:11456
	s_waitcnt lgkmcnt(6)
; __device__ void wf_task(int wv, const Params& p, int task, float* ldsf) {
;     ...
;     for (int cq = 0; cq < 128; ++cq) { const float v = tile[cq * 64 + n];
; #pragma unroll
;         for (int cc = 0; cc < 16; ++cc) { const int idx = ((wvl * 16 + cc) * cq) & 127; ac[cc] += ct[idx] * v; as[cc] += ct[(idx + 96) & 127] * v; } }
	v_mfma_f32_16x16x4_f32 v[2:5], v34, v38, v[2:5]
	v_mfma_f32_16x16x4_f32 v[18:21], v35, v38, v[18:21]
	v_mfma_f32_16x16x4_f32 v[6:9], v34, v39, v[6:9]
	v_mfma_f32_16x16x4_f32 v[22:25], v35, v39, v[22:25]
	v_mfma_f32_16x16x4_f32 v[10:13], v34, v40, v[10:13]
	v_mfma_f32_16x16x4_f32 v[26:29], v35, v40, v[26:29]
	v_mfma_f32_16x16x4_f32 v[14:17], v34, v41, v[14:17]
	v_mfma_f32_16x16x4_f32 v[30:33], v35, v41, v[30:33]
	v_add_u32_e32 v46, v46, v48
	v_and_b32_e32 v46, 0x1fc, v46
	v_add_u32_e32 v47, 0x180, v46
	v_and_b32_e32 v47, 0x1fc, v47
	ds_read_b32 v34, v46 offset:32768
	ds_read_b32 v35, v47 offset:32768
	ds_read_b32 v38, v49 offset:12288
	ds_read_b32 v39, v49 offset:12352
	ds_read_b32 v40, v49 offset:12416
	ds_read_b32 v41, v49 offset:12480
	s_waitcnt lgkmcnt(6)
	v_mfma_f32_16x16x4_f32 v[2:5], v36, v42, v[2:5]
	v_mfma_f32_16x16x4_f32 v[18:21], v37, v42, v[18:21]
	v_mfma_f32_16x16x4_f32 v[6:9], v36, v43, v[6:9]
	v_mfma_f32_16x16x4_f32 v[22:25], v37, v43, v[22:25]
	v_mfma_f32_16x16x4_f32 v[10:13], v36, v44, v[10:13]
	v_mfma_f32_16x16x4_f32 v[26:29], v37, v44, v[26:29]
	v_mfma_f32_16x16x4_f32 v[14:17], v36, v45, v[14:17]
	v_mfma_f32_16x16x4_f32 v[30:33], v37, v45, v[30:33]
	v_add_u32_e32 v46, v46, v48
	v_and_b32_e32 v46, 0x1fc, v46
	v_add_u32_e32 v47, 0x180, v46
	v_and_b32_e32 v47, 0x1fc, v47
	ds_read_b32 v36, v46 offset:32768
	ds_read_b32 v37, v47 offset:32768
	ds_read_b32 v42, v49 offset:13312
	ds_read_b32 v43, v49 offset:13376
	ds_read_b32 v44, v49 offset:13440
	ds_read_b32 v45, v49 offset:13504
	s_waitcnt lgkmcnt(6)
	v_mfma_f32_16x16x4_f32 v[2:5], v34, v38, v[2:5]
	v_mfma_f32_16x16x4_f32 v[18:21], v35, v38, v[18:21]
	v_mfma_f32_16x16x4_f32 v[6:9], v34, v39, v[6:9]
	v_mfma_f32_16x16x4_f32 v[22:25], v35, v39, v[22:25]
	v_mfma_f32_16x16x4_f32 v[10:13], v34, v40, v[10:13]
	v_mfma_f32_16x16x4_f32 v[26:29], v35, v40, v[26:29]
	v_mfma_f32_16x16x4_f32 v[14:17], v34, v41, v[14:17]
	v_mfma_f32_16x16x4_f32 v[30:33], v35, v41, v[30:33]
	v_add_u32_e32 v46, v46, v48
	v_and_b32_e32 v46, 0x1fc, v46
	v_add_u32_e32 v47, 0x180, v46
	v_and_b32_e32 v47, 0x1fc, v47
	ds_read_b32 v34, v46 offset:32768
	ds_read_b32 v35, v47 offset:32768
	ds_read_b32 v38, v49 offset:14336
	ds_read_b32 v39, v49 offset:14400
	ds_read_b32 v40, v49 offset:14464
	ds_read_b32 v41, v49 offset:14528
	s_waitcnt lgkmcnt(6)
	v_mfma_f32_16x16x4_f32 v[2:5], v36, v42, v[2:5]
	v_mfma_f32_16x16x4_f32 v[18:21], v37, v42, v[18:21]
	v_mfma_f32_16x16x4_f32 v[6:9], v36, v43, v[6:9]
	v_mfma_f32_16x16x4_f32 v[22:25], v37, v43, v[22:25]
	v_mfma_f32_16x16x4_f32 v[10:13], v36, v44, v[10:13]
	v_mfma_f32_16x16x4_f32 v[26:29], v37, v44, v[26:29]
	v_mfma_f32_16x16x4_f32 v[14:17], v36, v45, v[14:17]
	v_mfma_f32_16x16x4_f32 v[30:33], v37, v45, v[30:33]
	v_add_u32_e32 v46, v46, v48
	v_and_b32_e32 v46, 0x1fc, v46
	v_add_u32_e32 v47, 0x180, v46
	v_and_b32_e32 v47, 0x1fc, v47
	ds_read_b32 v36, v46 offset:32768
	ds_read_b32 v37, v47 offset:32768
	ds_read_b32 v42, v49 offset:15360
	ds_read_b32 v43, v49 offset:15424
	ds_read_b32 v44, v49 offset:15488
	ds_read_b32 v45, v49 offset:15552
	s_waitcnt lgkmcnt(6)
	v_mfma_f32_16x16x4_f32 v[2:5], v34, v38, v[2:5]
	v_mfma_f32_16x16x4_f32 v[18:21], v35, v38, v[18:21]
	v_mfma_f32_16x16x4_f32 v[6:9], v34, v39, v[6:9]
	v_mfma_f32_16x16x4_f32 v[22:25], v35, v39, v[22:25]
	v_mfma_f32_16x16x4_f32 v[10:13], v34, v40, v[10:13]
	v_mfma_f32_16x16x4_f32 v[26:29], v35, v40, v[26:29]
	v_mfma_f32_16x16x4_f32 v[14:17], v34, v41, v[14:17]
	v_mfma_f32_16x16x4_f32 v[30:33], v35, v41, v[30:33]
	v_add_u32_e32 v46, v46, v48
	v_and_b32_e32 v46, 0x1fc, v46
	v_add_u32_e32 v47, 0x180, v46
	v_and_b32_e32 v47, 0x1fc, v47
	ds_read_b32 v34, v46 offset:32768
	ds_read_b32 v35, v47 offset:32768
	ds_read_b32 v38, v49 offset:16384
	ds_read_b32 v39, v49 offset:16448
	ds_read_b32 v40, v49 offset:16512
	ds_read_b32 v41, v49 offset:16576
	s_waitcnt lgkmcnt(6)
	v_mfma_f32_16x16x4_f32 v[2:5], v36, v42, v[2:5]
	v_mfma_f32_16x16x4_f32 v[18:21], v37, v42, v[18:21]
	v_mfma_f32_16x16x4_f32 v[6:9], v36, v43, v[6:9]
	v_mfma_f32_16x16x4_f32 v[22:25], v37, v43, v[22:25]
	v_mfma_f32_16x16x4_f32 v[10:13], v36, v44, v[10:13]
	v_mfma_f32_16x16x4_f32 v[26:29], v37, v44, v[26:29]
	v_mfma_f32_16x16x4_f32 v[14:17], v36, v45, v[14:17]
	v_mfma_f32_16x16x4_f32 v[30:33], v37, v45, v[30:33]
	v_add_u32_e32 v46, v46, v48
	v_and_b32_e32 v46, 0x1fc, v46
	v_add_u32_e32 v47, 0x180, v46
	v_and_b32_e32 v47, 0x1fc, v47
	ds_read_b32 v36, v46 offset:32768
	ds_read_b32 v37, v47 offset:32768
	ds_read_b32 v42, v49 offset:17408
	ds_read_b32 v43, v49 offset:17472
	ds_read_b32 v44, v49 offset:17536
	ds_read_b32 v45, v49 offset:17600
	s_waitcnt lgkmcnt(6)
	v_mfma_f32_16x16x4_f32 v[2:5], v34, v38, v[2:5]
	v_mfma_f32_16x16x4_f32 v[18:21], v35, v38, v[18:21]
	v_mfma_f32_16x16x4_f32 v[6:9], v34, v39, v[6:9]
	v_mfma_f32_16x16x4_f32 v[22:25], v35, v39, v[22:25]
	v_mfma_f32_16x16x4_f32 v[10:13], v34, v40, v[10:13]
	v_mfma_f32_16x16x4_f32 v[26:29], v35, v40, v[26:29]
	v_mfma_f32_16x16x4_f32 v[14:17], v34, v41, v[14:17]
	v_mfma_f32_16x16x4_f32 v[30:33], v35, v41, v[30:33]
	v_add_u32_e32 v46, v46, v48
	v_and_b32_e32 v46, 0x1fc, v46
	v_add_u32_e32 v47, 0x180, v46
	v_and_b32_e32 v47, 0x1fc, v47
	ds_read_b32 v34, v46 offset:32768
	ds_read_b32 v35, v47 offset:32768
	ds_read_b32 v38, v49 offset:18432
	ds_read_b32 v39, v49 offset:18496
	ds_read_b32 v40, v49 offset:18560
	ds_read_b32 v41, v49 offset:18624
	s_waitcnt lgkmcnt(6)
; __device__ void wf_task(int wv, const Params& p, int task, float* ldsf) {
;     ...
;     for (int cq = 0; cq < 128; ++cq) { const float v = tile[cq * 64 + n];
; #pragma unroll
;         for (int cc = 0; cc < 16; ++cc) { const int idx = ((wvl * 16 + cc) * cq) & 127; ac[cc] += ct[idx] * v; as[cc] += ct[(idx + 96) & 127] * v; } }
	v_mfma_f32_16x16x4_f32 v[2:5], v36, v42, v[2:5]
	v_mfma_f32_16x16x4_f32 v[18:21], v37, v42, v[18:21]
	v_mfma_f32_16x16x4_f32 v[6:9], v36, v43, v[6:9]
	v_mfma_f32_16x16x4_f32 v[22:25], v37, v43, v[22:25]
	v_mfma_f32_16x16x4_f32 v[10:13], v36, v44, v[10:13]
	v_mfma_f32_16x16x4_f32 v[26:29], v37, v44, v[26:29]
	v_mfma_f32_16x16x4_f32 v[14:17], v36, v45, v[14:17]
	v_mfma_f32_16x16x4_f32 v[30:33], v37, v45, v[30:33]
	v_add_u32_e32 v46, v46, v48
	v_and_b32_e32 v46, 0x1fc, v46
	v_add_u32_e32 v47, 0x180, v46
	v_and_b32_e32 v47, 0x1fc, v47
	ds_read_b32 v36, v46 offset:32768
	ds_read_b32 v37, v47 offset:32768
	ds_read_b32 v42, v49 offset:19456
	ds_read_b32 v43, v49 offset:19520
	ds_read_b32 v44, v49 offset:19584
	ds_read_b32 v45, v49 offset:19648
	s_waitcnt lgkmcnt(6)
	v_mfma_f32_16x16x4_f32 v[2:5], v34, v38, v[2:5]
	v_mfma_f32_16x16x4_f32 v[18:21], v35, v38, v[18:21]
	v_mfma_f32_16x16x4_f32 v[6:9], v34, v39, v[6:9]
	v_mfma_f32_16x16x4_f32 v[22:25], v35, v39, v[22:25]
	v_mfma_f32_16x16x4_f32 v[10:13], v34, v40, v[10:13]
	v_mfma_f32_16x16x4_f32 v[26:29], v35, v40, v[26:29]
	v_mfma_f32_16x16x4_f32 v[14:17], v34, v41, v[14:17]
	v_mfma_f32_16x16x4_f32 v[30:33], v35, v41, v[30:33]
	v_add_u32_e32 v46, v46, v48
	v_and_b32_e32 v46, 0x1fc, v46
	v_add_u32_e32 v47, 0x180, v46
	v_and_b32_e32 v47, 0x1fc, v47
	ds_read_b32 v34, v46 offset:32768
	ds_read_b32 v35, v47 offset:32768
	ds_read_b32 v38, v49 offset:20480
	ds_read_b32 v39, v49 offset:20544
	ds_read_b32 v40, v49 offset:20608
	ds_read_b32 v41, v49 offset:20672
	s_waitcnt lgkmcnt(6)
	v_mfma_f32_16x16x4_f32 v[2:5], v36, v42, v[2:5]
	v_mfma_f32_16x16x4_f32 v[18:21], v37, v42, v[18:21]
	v_mfma_f32_16x16x4_f32 v[6:9], v36, v43, v[6:9]
	v_mfma_f32_16x16x4_f32 v[22:25], v37, v43, v[22:25]
	v_mfma_f32_16x16x4_f32 v[10:13], v36, v44, v[10:13]
	v_mfma_f32_16x16x4_f32 v[26:29], v37, v44, v[26:29]
	v_mfma_f32_16x16x4_f32 v[14:17], v36, v45, v[14:17]
	v_mfma_f32_16x16x4_f32 v[30:33], v37, v45, v[30:33]
	v_add_u32_e32 v46, v46, v48
	v_and_b32_e32 v46, 0x1fc, v46
	v_add_u32_e32 v47, 0x180, v46
	v_and_b32_e32 v47, 0x1fc, v47
	ds_read_b32 v36, v46 offset:32768
	ds_read_b32 v37, v47 offset:32768
	ds_read_b32 v42, v49 offset:21504
	ds_read_b32 v43, v49 offset:21568
	ds_read_b32 v44, v49 offset:21632
	ds_read_b32 v45, v49 offset:21696
	s_waitcnt lgkmcnt(6)
	v_mfma_f32_16x16x4_f32 v[2:5], v34, v38, v[2:5]
	v_mfma_f32_16x16x4_f32 v[18:21], v35, v38, v[18:21]
	v_mfma_f32_16x16x4_f32 v[6:9], v34, v39, v[6:9]
	v_mfma_f32_16x16x4_f32 v[22:25], v35, v39, v[22:25]
	v_mfma_f32_16x16x4_f32 v[10:13], v34, v40, v[10:13]
	v_mfma_f32_16x16x4_f32 v[26:29], v35, v40, v[26:29]
	v_mfma_f32_16x16x4_f32 v[14:17], v34, v41, v[14:17]
	v_mfma_f32_16x16x4_f32 v[30:33], v35, v41, v[30:33]
	v_add_u32_e32 v46, v46, v48
	v_and_b32_e32 v46, 0x1fc, v46
	v_add_u32_e32 v47, 0x180, v46
	v_and_b32_e32 v47, 0x1fc, v47
	ds_read_b32 v34, v46 offset:32768
	ds_read_b32 v35, v47 offset:32768
	ds_read_b32 v38, v49 offset:22528
	ds_read_b32 v39, v49 offset:22592
	ds_read_b32 v40, v49 offset:22656
	ds_read_b32 v41, v49 offset:22720
	s_waitcnt lgkmcnt(6)
	v_mfma_f32_16x16x4_f32 v[2:5], v36, v42, v[2:5]
	v_mfma_f32_16x16x4_f32 v[18:21], v37, v42, v[18:21]
	v_mfma_f32_16x16x4_f32 v[6:9], v36, v43, v[6:9]
	v_mfma_f32_16x16x4_f32 v[22:25], v37, v43, v[22:25]
	v_mfma_f32_16x16x4_f32 v[10:13], v36, v44, v[10:13]
	v_mfma_f32_16x16x4_f32 v[26:29], v37, v44, v[26:29]
	v_mfma_f32_16x16x4_f32 v[14:17], v36, v45, v[14:17]
	v_mfma_f32_16x16x4_f32 v[30:33], v37, v45, v[30:33]
	v_add_u32_e32 v46, v46, v48
	v_and_b32_e32 v46, 0x1fc, v46
	v_add_u32_e32 v47, 0x180, v46
	v_and_b32_e32 v47, 0x1fc, v47
	ds_read_b32 v36, v46 offset:32768
	ds_read_b32 v37, v47 offset:32768
	ds_read_b32 v42, v49 offset:23552
	ds_read_b32 v43, v49 offset:23616
	ds_read_b32 v44, v49 offset:23680
	ds_read_b32 v45, v49 offset:23744
	s_waitcnt lgkmcnt(6)
	v_mfma_f32_16x16x4_f32 v[2:5], v34, v38, v[2:5]
	v_mfma_f32_16x16x4_f32 v[18:21], v35, v38, v[18:21]
	v_mfma_f32_16x16x4_f32 v[6:9], v34, v39, v[6:9]
	v_mfma_f32_16x16x4_f32 v[22:25], v35, v39, v[22:25]
	v_mfma_f32_16x16x4_f32 v[10:13], v34, v40, v[10:13]
	v_mfma_f32_16x16x4_f32 v[26:29], v35, v40, v[26:29]
	v_mfma_f32_16x16x4_f32 v[14:17], v34, v41, v[14:17]
	v_mfma_f32_16x16x4_f32 v[30:33], v35, v41, v[30:33]
	v_add_u32_e32 v46, v46, v48
	v_and_b32_e32 v46, 0x1fc, v46
	v_add_u32_e32 v47, 0x180, v46
	v_and_b32_e32 v47, 0x1fc, v47
	ds_read_b32 v34, v46 offset:32768
	ds_read_b32 v35, v47 offset:32768
	ds_read_b32 v38, v49 offset:24576
	ds_read_b32 v39, v49 offset:24640
	ds_read_b32 v40, v49 offset:24704
	ds_read_b32 v41, v49 offset:24768
	s_waitcnt lgkmcnt(6)
	v_mfma_f32_16x16x4_f32 v[2:5], v36, v42, v[2:5]
	v_mfma_f32_16x16x4_f32 v[18:21], v37, v42, v[18:21]
	v_mfma_f32_16x16x4_f32 v[6:9], v36, v43, v[6:9]
	v_mfma_f32_16x16x4_f32 v[22:25], v37, v43, v[22:25]
	v_mfma_f32_16x16x4_f32 v[10:13], v36, v44, v[10:13]
	v_mfma_f32_16x16x4_f32 v[26:29], v37, v44, v[26:29]
	v_mfma_f32_16x16x4_f32 v[14:17], v36, v45, v[14:17]
	v_mfma_f32_16x16x4_f32 v[30:33], v37, v45, v[30:33]
	v_add_u32_e32 v46, v46, v48
	v_and_b32_e32 v46, 0x1fc, v46
	v_add_u32_e32 v47, 0x180, v46
	v_and_b32_e32 v47, 0x1fc, v47
	ds_read_b32 v36, v46 offset:32768
	ds_read_b32 v37, v47 offset:32768
	ds_read_b32 v42, v49 offset:25600
	ds_read_b32 v43, v49 offset:25664
	ds_read_b32 v44, v49 offset:25728
	ds_read_b32 v45, v49 offset:25792
	s_waitcnt lgkmcnt(6)
; __device__ void wf_task(int wv, const Params& p, int task, float* ldsf) {
;     ...
;     for (int cq = 0; cq < 128; ++cq) { const float v = tile[cq * 64 + n];
; #pragma unroll
;         for (int cc = 0; cc < 16; ++cc) { const int idx = ((wvl * 16 + cc) * cq) & 127; ac[cc] += ct[idx] * v; as[cc] += ct[(idx + 96) & 127] * v; } }
	v_mfma_f32_16x16x4_f32 v[2:5], v34, v38, v[2:5]
	v_mfma_f32_16x16x4_f32 v[18:21], v35, v38, v[18:21]
	v_mfma_f32_16x16x4_f32 v[6:9], v34, v39, v[6:9]
	v_mfma_f32_16x16x4_f32 v[22:25], v35, v39, v[22:25]
	v_mfma_f32_16x16x4_f32 v[10:13], v34, v40, v[10:13]
	v_mfma_f32_16x16x4_f32 v[26:29], v35, v40, v[26:29]
	v_mfma_f32_16x16x4_f32 v[14:17], v34, v41, v[14:17]
	v_mfma_f32_16x16x4_f32 v[30:33], v35, v41, v[30:33]
	v_add_u32_e32 v46, v46, v48
	v_and_b32_e32 v46, 0x1fc, v46
	v_add_u32_e32 v47, 0x180, v46
	v_and_b32_e32 v47, 0x1fc, v47
	ds_read_b32 v34, v46 offset:32768
	ds_read_b32 v35, v47 offset:32768
	ds_read_b32 v38, v49 offset:26624
	ds_read_b32 v39, v49 offset:26688
	ds_read_b32 v40, v49 offset:26752
	ds_read_b32 v41, v49 offset:26816
	s_waitcnt lgkmcnt(6)
	v_mfma_f32_16x16x4_f32 v[2:5], v36, v42, v[2:5]
	v_mfma_f32_16x16x4_f32 v[18:21], v37, v42, v[18:21]
	v_mfma_f32_16x16x4_f32 v[6:9], v36, v43, v[6:9]
	v_mfma_f32_16x16x4_f32 v[22:25], v37, v43, v[22:25]
	v_mfma_f32_16x16x4_f32 v[10:13], v36, v44, v[10:13]
	v_mfma_f32_16x16x4_f32 v[26:29], v37, v44, v[26:29]
	v_mfma_f32_16x16x4_f32 v[14:17], v36, v45, v[14:17]
	v_mfma_f32_16x16x4_f32 v[30:33], v37, v45, v[30:33]
	v_add_u32_e32 v46, v46, v48
	v_and_b32_e32 v46, 0x1fc, v46
	v_add_u32_e32 v47, 0x180, v46
	v_and_b32_e32 v47, 0x1fc, v47
	ds_read_b32 v36, v46 offset:32768
	ds_read_b32 v37, v47 offset:32768
	ds_read_b32 v42, v49 offset:27648
	ds_read_b32 v43, v49 offset:27712
	ds_read_b32 v44, v49 offset:27776
	ds_read_b32 v45, v49 offset:27840
	s_waitcnt lgkmcnt(6)
	v_mfma_f32_16x16x4_f32 v[2:5], v34, v38, v[2:5]
	v_mfma_f32_16x16x4_f32 v[18:21], v35, v38, v[18:21]
	v_mfma_f32_16x16x4_f32 v[6:9], v34, v39, v[6:9]
	v_mfma_f32_16x16x4_f32 v[22:25], v35, v39, v[22:25]
	v_mfma_f32_16x16x4_f32 v[10:13], v34, v40, v[10:13]
	v_mfma_f32_16x16x4_f32 v[26:29], v35, v40, v[26:29]
	v_mfma_f32_16x16x4_f32 v[14:17], v34, v41, v[14:17]
	v_mfma_f32_16x16x4_f32 v[30:33], v35, v41, v[30:33]
	v_add_u32_e32 v46, v46, v48
	v_and_b32_e32 v46, 0x1fc, v46
	v_add_u32_e32 v47, 0x180, v46
	v_and_b32_e32 v47, 0x1fc, v47
	ds_read_b32 v34, v46 offset:32768
	ds_read_b32 v35, v47 offset:32768
	ds_read_b32 v38, v49 offset:28672
	ds_read_b32 v39, v49 offset:28736
	ds_read_b32 v40, v49 offset:28800
	ds_read_b32 v41, v49 offset:28864
	s_waitcnt lgkmcnt(6)
	v_mfma_f32_16x16x4_f32 v[2:5], v36, v42, v[2:5]
	v_mfma_f32_16x16x4_f32 v[18:21], v37, v42, v[18:21]
	v_mfma_f32_16x16x4_f32 v[6:9], v36, v43, v[6:9]
	v_mfma_f32_16x16x4_f32 v[22:25], v37, v43, v[22:25]
	v_mfma_f32_16x16x4_f32 v[10:13], v36, v44, v[10:13]
	v_mfma_f32_16x16x4_f32 v[26:29], v37, v44, v[26:29]
	v_mfma_f32_16x16x4_f32 v[14:17], v36, v45, v[14:17]
	v_mfma_f32_16x16x4_f32 v[30:33], v37, v45, v[30:33]
	v_add_u32_e32 v46, v46, v48
	v_and_b32_e32 v46, 0x1fc, v46
	v_add_u32_e32 v47, 0x180, v46
	v_and_b32_e32 v47, 0x1fc, v47
	ds_read_b32 v36, v46 offset:32768
	ds_read_b32 v37, v47 offset:32768
	ds_read_b32 v42, v49 offset:29696
	ds_read_b32 v43, v49 offset:29760
	ds_read_b32 v44, v49 offset:29824
	ds_read_b32 v45, v49 offset:29888
	s_waitcnt lgkmcnt(6)
	v_mfma_f32_16x16x4_f32 v[2:5], v34, v38, v[2:5]
	v_mfma_f32_16x16x4_f32 v[18:21], v35, v38, v[18:21]
	v_mfma_f32_16x16x4_f32 v[6:9], v34, v39, v[6:9]
	v_mfma_f32_16x16x4_f32 v[22:25], v35, v39, v[22:25]
	v_mfma_f32_16x16x4_f32 v[10:13], v34, v40, v[10:13]
	v_mfma_f32_16x16x4_f32 v[26:29], v35, v40, v[26:29]
	v_mfma_f32_16x16x4_f32 v[14:17], v34, v41, v[14:17]
	v_mfma_f32_16x16x4_f32 v[30:33], v35, v41, v[30:33]
	v_add_u32_e32 v46, v46, v48
	v_and_b32_e32 v46, 0x1fc, v46
	v_add_u32_e32 v47, 0x180, v46
	v_and_b32_e32 v47, 0x1fc, v47
	ds_read_b32 v34, v46 offset:32768
	ds_read_b32 v35, v47 offset:32768
	ds_read_b32 v38, v49 offset:30720
	ds_read_b32 v39, v49 offset:30784
	ds_read_b32 v40, v49 offset:30848
	ds_read_b32 v41, v49 offset:30912
	s_waitcnt lgkmcnt(6)
; __device__ void wf_task(int wv, const Params& p, int task, float* ldsf) {
;     ...
;     for (int cq = 0; cq < 128; ++cq) { const float v = tile[cq * 64 + n];
; #pragma unroll
;         for (int cc = 0; cc < 16; ++cc) { const int idx = ((wvl * 16 + cc) * cq) & 127; ac[cc] += ct[idx] * v; as[cc] += ct[(idx + 96) & 127] * v; } }
;     float* Wf = (float*)(p.ws + WS_WF32);
; #pragma unroll
;     for (int cc = 0; cc < 16; ++cc) { const int c = wvl * 16 + cc; Wf[(size_t)(g * 128 + c) * DM + n0 + n] = ac[cc]; Wf[(size_t)(1024 + g * 128 + c) * DM + n0 + n] = as[cc]; }
;     __syncthreads();
	v_mfma_f32_16x16x4_f32 v[2:5], v36, v42, v[2:5]
	v_mfma_f32_16x16x4_f32 v[18:21], v37, v42, v[18:21]
	v_mfma_f32_16x16x4_f32 v[6:9], v36, v43, v[6:9]
	v_mfma_f32_16x16x4_f32 v[22:25], v37, v43, v[22:25]
	v_mfma_f32_16x16x4_f32 v[10:13], v36, v44, v[10:13]
	v_mfma_f32_16x16x4_f32 v[26:29], v37, v44, v[26:29]
	v_mfma_f32_16x16x4_f32 v[14:17], v36, v45, v[14:17]
	v_mfma_f32_16x16x4_f32 v[30:33], v37, v45, v[30:33]
	v_add_u32_e32 v46, v46, v48
	v_and_b32_e32 v46, 0x1fc, v46
	v_add_u32_e32 v47, 0x180, v46
	v_and_b32_e32 v47, 0x1fc, v47
	ds_read_b32 v36, v46 offset:32768
	ds_read_b32 v37, v47 offset:32768
	ds_read_b32 v42, v49 offset:31744
	ds_read_b32 v43, v49 offset:31808
	ds_read_b32 v44, v49 offset:31872
	ds_read_b32 v45, v49 offset:31936
	s_waitcnt lgkmcnt(6)
	v_mfma_f32_16x16x4_f32 v[2:5], v34, v38, v[2:5]
	v_mfma_f32_16x16x4_f32 v[18:21], v35, v38, v[18:21]
	v_mfma_f32_16x16x4_f32 v[6:9], v34, v39, v[6:9]
	v_mfma_f32_16x16x4_f32 v[22:25], v35, v39, v[22:25]
	v_mfma_f32_16x16x4_f32 v[10:13], v34, v40, v[10:13]
	v_mfma_f32_16x16x4_f32 v[26:29], v35, v40, v[26:29]
	v_mfma_f32_16x16x4_f32 v[14:17], v34, v41, v[14:17]
	v_mfma_f32_16x16x4_f32 v[30:33], v35, v41, v[30:33]
	s_waitcnt lgkmcnt(0)
	v_mfma_f32_16x16x4_f32 v[2:5], v36, v42, v[2:5]
	v_mfma_f32_16x16x4_f32 v[18:21], v37, v42, v[18:21]
	v_mfma_f32_16x16x4_f32 v[6:9], v36, v43, v[6:9]
	v_mfma_f32_16x16x4_f32 v[22:25], v37, v43, v[22:25]
	v_mfma_f32_16x16x4_f32 v[10:13], v36, v44, v[10:13]
	v_mfma_f32_16x16x4_f32 v[26:29], v37, v44, v[26:29]
	v_mfma_f32_16x16x4_f32 v[14:17], v36, v45, v[14:17]
	v_mfma_f32_16x16x4_f32 v[30:33], v37, v45, v[30:33]
	s_lshl_b32 s38, s10, 7
	s_lshl_b32 s39, s33, 4
	s_add_i32 s38, s38, s39
	v_lshl_add_u32 v54, v56, 2, s38
	v_lshlrev_b32_e32 v54, 12, v54
	v_add_u32_e32 v55, s11, v55
	v_lshl_add_u32 v50, v55, 2, v54
	v_add_u32_e32 v51, 0x1000, v50
	v_add_u32_e32 v52, 0x2000, v50
	v_add_u32_e32 v53, 0x3000, v50
	s_add_u32 s44, s30, 0x3ec600
	s_addc_u32 s45, s31, 0
	s_add_u32 s38, s44, 0x400000
	s_addc_u32 s39, s45, 0
	s_nop 7
	s_nop 3
	global_store_dword v50, v2, s[44:45]
	global_store_dword v50, v18, s[38:39]
	global_store_dword v51, v3, s[44:45]
	global_store_dword v51, v19, s[38:39]
	global_store_dword v52, v4, s[44:45]
	global_store_dword v52, v20, s[38:39]
	global_store_dword v53, v5, s[44:45]
	global_store_dword v53, v21, s[38:39]
	global_store_dword v50, v6, s[44:45] offset:64
	global_store_dword v50, v22, s[38:39] offset:64
	global_store_dword v51, v7, s[44:45] offset:64
	global_store_dword v51, v23, s[38:39] offset:64
	global_store_dword v52, v8, s[44:45] offset:64
	global_store_dword v52, v24, s[38:39] offset:64
	global_store_dword v53, v9, s[44:45] offset:64
	global_store_dword v53, v25, s[38:39] offset:64
	global_store_dword v50, v10, s[44:45] offset:128
	global_store_dword v50, v26, s[38:39] offset:128
	global_store_dword v51, v11, s[44:45] offset:128
	global_store_dword v51, v27, s[38:39] offset:128
	global_store_dword v52, v12, s[44:45] offset:128
	global_store_dword v52, v28, s[38:39] offset:128
	global_store_dword v53, v13, s[44:45] offset:128
	global_store_dword v53, v29, s[38:39] offset:128
	global_store_dword v50, v14, s[44:45] offset:192
	global_store_dword v50, v30, s[38:39] offset:192
	global_store_dword v51, v15, s[44:45] offset:192
	global_store_dword v51, v31, s[38:39] offset:192
	global_store_dword v52, v16, s[44:45] offset:192
	global_store_dword v52, v32, s[38:39] offset:192
	global_store_dword v53, v17, s[44:45] offset:192
	global_store_dword v53, v33, s[38:39] offset:192
	s_mov_b64 s[82:83], s[92:93]
	s_barrier
